# MLP-up epilogue: first two row-sumsq loads issued before the K loop (hidden behind the mainloop)
# speedup vs baseline: 1.1059x; 1.0027x over previous
.LBB0_2427:
	s_ashr_i32 s47, s46, 31
	s_lshl_b64 s[20:21], s[46:47], 19
	s_add_u32 s50, s54, s20
	s_addc_u32 s51, s55, s21
	s_and_b64 s[4:5], s[4:5], exec
	s_cselect_b32 s7, s51, s9
	s_cselect_b32 s47, s50, s8
	s_add_u32 s4, s52, 0x40080
	s_addc_u32 s5, s53, 0
	s_add_u32 s68, s8, 0x100
	v_mov_b32_e32 v2, 0
	s_addc_u32 s69, s9, 0
	s_mov_b32 s70, -2
	v_mov_b32_e32 v3, v2
	v_mov_b32_e32 v4, v2
	v_mov_b32_e32 v5, v2
	v_mov_b32_e32 v6, v2
	v_mov_b32_e32 v7, v2
	v_mov_b32_e32 v8, v2
	v_mov_b32_e32 v9, v2
	v_mov_b32_e32 v18, v2
	v_mov_b32_e32 v19, v2
	v_mov_b32_e32 v20, v2
	v_mov_b32_e32 v21, v2
	v_mov_b32_e32 v22, v2
	v_mov_b32_e32 v23, v2
	v_mov_b32_e32 v24, v2
	v_mov_b32_e32 v25, v2
	v_mov_b32_e32 v34, v2
	v_mov_b32_e32 v35, v2
	v_mov_b32_e32 v36, v2
	v_mov_b32_e32 v37, v2
	v_mov_b32_e32 v38, v2
	v_mov_b32_e32 v39, v2
	v_mov_b32_e32 v40, v2
	v_mov_b32_e32 v41, v2
	v_mov_b32_e32 v50, v2
	v_mov_b32_e32 v51, v2
	v_mov_b32_e32 v52, v2
	v_mov_b32_e32 v53, v2
	v_mov_b32_e32 v54, v2
	v_mov_b32_e32 v55, v2
	v_mov_b32_e32 v56, v2
	v_mov_b32_e32 v57, v2
	v_mov_b32_e32 v10, v2
	v_mov_b32_e32 v11, v2
	v_mov_b32_e32 v12, v2
	v_mov_b32_e32 v13, v2
	v_mov_b32_e32 v14, v2
	v_mov_b32_e32 v15, v2
	v_mov_b32_e32 v16, v2
	v_mov_b32_e32 v17, v2
	v_mov_b32_e32 v26, v2
	v_mov_b32_e32 v27, v2
	v_mov_b32_e32 v28, v2
	v_mov_b32_e32 v29, v2
	v_mov_b32_e32 v30, v2
	v_mov_b32_e32 v31, v2
	v_mov_b32_e32 v32, v2
	v_mov_b32_e32 v33, v2
	v_mov_b32_e32 v42, v2
	v_mov_b32_e32 v43, v2
	v_mov_b32_e32 v44, v2
	v_mov_b32_e32 v45, v2
	v_mov_b32_e32 v46, v2
	v_mov_b32_e32 v47, v2
	v_mov_b32_e32 v48, v2
	v_mov_b32_e32 v49, v2
	v_mov_b32_e32 v58, v2
	v_mov_b32_e32 v59, v2
	v_mov_b32_e32 v60, v2
	v_mov_b32_e32 v61, v2
	v_mov_b32_e32 v62, v2
	v_mov_b32_e32 v63, v2
	v_mov_b32_e32 v64, v2
	v_mov_b32_e32 v65, v2
	v_mov_b32_e32 v66, v2
	v_mov_b32_e32 v67, v2
	v_mov_b32_e32 v68, v2
	v_mov_b32_e32 v69, v2
	v_mov_b32_e32 v70, v2
	v_mov_b32_e32 v71, v2
	v_mov_b32_e32 v72, v2
	v_mov_b32_e32 v73, v2
	v_mov_b32_e32 v82, v2
	v_mov_b32_e32 v83, v2
	v_mov_b32_e32 v84, v2
	v_mov_b32_e32 v85, v2
	v_mov_b32_e32 v86, v2
	v_mov_b32_e32 v87, v2
	v_mov_b32_e32 v88, v2
	v_mov_b32_e32 v89, v2
	v_mov_b32_e32 v98, v2
	v_mov_b32_e32 v99, v2
	v_mov_b32_e32 v100, v2
	v_mov_b32_e32 v101, v2
	v_mov_b32_e32 v102, v2
	v_mov_b32_e32 v103, v2
	v_mov_b32_e32 v104, v2
	v_mov_b32_e32 v105, v2
	v_mov_b32_e32 v114, v2
	v_mov_b32_e32 v115, v2
	v_mov_b32_e32 v116, v2
	v_mov_b32_e32 v117, v2
	v_mov_b32_e32 v118, v2
	v_mov_b32_e32 v119, v2
	v_mov_b32_e32 v120, v2
	v_mov_b32_e32 v121, v2
	v_mov_b32_e32 v74, v2
	v_mov_b32_e32 v75, v2
	v_mov_b32_e32 v76, v2
	v_mov_b32_e32 v77, v2
	v_mov_b32_e32 v78, v2
	v_mov_b32_e32 v79, v2
	v_mov_b32_e32 v80, v2
	v_mov_b32_e32 v81, v2
	v_mov_b32_e32 v90, v2
	v_mov_b32_e32 v91, v2
	v_mov_b32_e32 v92, v2
	v_mov_b32_e32 v93, v2
	v_mov_b32_e32 v94, v2
	v_mov_b32_e32 v95, v2
	v_mov_b32_e32 v96, v2
	v_mov_b32_e32 v97, v2
	v_mov_b32_e32 v106, v2
	v_mov_b32_e32 v107, v2
	v_mov_b32_e32 v108, v2
	v_mov_b32_e32 v109, v2
	v_mov_b32_e32 v110, v2
	v_mov_b32_e32 v111, v2
	v_mov_b32_e32 v112, v2
	v_mov_b32_e32 v113, v2
	v_mov_b32_e32 v122, v2
	v_mov_b32_e32 v123, v2
	v_mov_b32_e32 v124, v2
	v_mov_b32_e32 v125, v2
	v_mov_b32_e32 v126, v2
	v_mov_b32_e32 v127, v2
	v_mov_b32_e32 v128, v2
	v_mov_b32_e32 v129, v2
	v_lshl_add_u32 v252, s67, 8, v146
	v_ashrrev_i32_e32 v253, 31, v252
	v_lshlrev_b64 v[248:249], 6, v[252:253]
	v_lshl_add_u64 v[248:249], s[18:19], 0, v[248:249]
	v_mbcnt_lo_u32_b32 v252, -1, 0
	v_mbcnt_hi_u32_b32 v252, -1, v252
	v_and_b32_e32 v252, 0x30, v252
	v_mov_b32_e32 v253, 0
	v_lshl_add_u64 v[248:249], v[248:249], 0, v[252:253]
	s_mov_b64 s[100:101], 0x2000
	v_lshl_add_u64 v[250:251], v[248:249], 0, s[100:101]
	global_load_dwordx4 v[232:235], v[248:249], off
	global_load_dwordx4 v[220:223], v[248:249], off offset:1024

.LBB0_2431:
	v_lshl_add_u32 v142, s67, 8, v146
	v_ashrrev_i32_e32 v143, 31, v142
	v_lshlrev_b64 v[140:141], 6, v[142:143]
	v_lshl_add_u64 v[140:141], s[18:19], 0, v[140:141]
	v_add_f32_e32 v216, v232, v233
	v_add_f32_e32 v218, v234, v235
	v_add_f32_e32 v216, v216, v218
	v_mov_b32_e32 v252, v216
	s_nop 1
	v_permlane16_swap_b32_e32 v252, v216
	v_add_f32_e32 v216, v216, v252
	v_mov_b32_e32 v252, v216
	s_nop 1
	v_permlane32_swap_b32_e32 v252, v216
	v_add_f32_e32 v140, v216, v252
	v_fmamk_f32 v140, v140, 0x3a800000, v212
	v_rsq_f32_e32 v224, v140
	s_nop 0
	v_mul_f32_e32 v225, v140, v224
	v_fma_f32 v225, -v225, v224, 1.0
	v_mul_f32_e32 v226, 0.5, v224
	v_lshl_or_b32 v140, s6, 8, v148
	v_cmp_gt_i32_e64 s[4:5], 2.0, v140
	v_ashrrev_i32_e32 v141, 31, v140
	v_lshlrev_b64 v[150:151], 13, v[142:143]
	s_nop 0
	v_fma_f32 v144, v226, v225, v224
	v_pk_mul_f32 v[128:129], v[128:129], v[144:145] op_sel_hi:[1,0]
	v_pk_mul_f32 v[126:127], v[126:127], v[144:145] op_sel_hi:[1,0]
	v_pk_mul_f32 v[124:125], v[124:125], v[144:145] op_sel_hi:[1,0]
	v_pk_mul_f32 v[122:123], v[122:123], v[144:145] op_sel_hi:[1,0]
	v_max_f32_e32 v126, 0, v126
	v_max_f32_e32 v122, 0, v122
	v_max_f32_e32 v127, 0, v127
	v_max_f32_e32 v123, 0, v123
	v_max_f32_e32 v128, 0, v128
	v_max_f32_e32 v124, 0, v124
	v_max_f32_e32 v129, 0, v129
	v_max_f32_e32 v125, 0, v125
	v_mul_f32_e32 v126, v126, v126
	v_mul_f32_e32 v143, v122, v122
	v_mul_f32_e32 v122, v127, v127
	v_mul_f32_e32 v127, v123, v123
	v_mul_f32_e32 v123, v128, v128
	v_mul_f32_e32 v128, v124, v124
	v_mul_f32_e32 v124, v129, v129
	v_mul_f32_e32 v125, v125, v125
	v_cvt_pk_bf16_f32 v122, v126, v122
	v_cvt_pk_bf16_f32 v123, v123, v124
	v_cvt_pk_bf16_f32 v124, v143, v127
	v_lshl_add_u64 v[126:127], s[40:41], 0, v[150:151]
	v_cvt_pk_bf16_f32 v125, v128, v125
	s_and_saveexec_b64 s[6:7], s[4:5]
	s_cbranch_execz .LBB0_2433
	v_lshl_add_u64 v[128:129], v[140:141], 1, v[126:127]
	global_store_dwordx4 v[128:129], v[122:125], off nt
